# slot-1 weight conversion handed to workgroups 0..127 (after their v tile); 128..255 only run their gating unit before the seam
# baseline (speedup 1.0000x reference)
.Ls2_done:
.LBB0_874:
	v_readlane_b32 s4, v252, 0
	v_readlane_b32 s5, v252, 1
	s_cmp_lt_u32 s2, 0x80
	s_cselect_b64 s[6:7], -1, 0
	s_and_b64 s[4:5], s[4:5], s[6:7]
	s_andn2_b64 vcc, exec, s[4:5]
	s_cbranch_vccnz .LBB0_1022
	v_mov_b32_e32 v0, v210
	s_mov_b64 s[28:29], -1
	v_readfirstlane_b32 s4, v0
	v_and_b32_e32 v141, 63, v0
	s_ashr_i32 s7, s4, 6
	s_lshl_b32 s4, s2, 3
	v_lshlrev_b32_e32 v2, 2, v141
	s_add_i32 s4, s7, s4
	s_cmpk_lt_i32 s4, 0x100
	v_lshrrev_b32_e32 v130, 4, v141
	v_and_b32_e32 v132, 60, v2
	s_movk_i32 s19, 0xb00
	s_cbranch_scc1 .LBB0_877
	v_lshrrev_b32_e32 v0, 4, v141
	v_and_b32_e32 v66, 60, v2
	v_mov_b32_e32 v67, v1
	s_mov_b64 s[28:29], 0
	v_mov_b64_e32 v[134:135], v[66:67]
	v_mov_b64_e32 v[136:137], v[0:1]
